# lambda vectors loaded up front in both LRU directions (per-group waits removed, last group wait kept for the loop entry invariant)
# speedup vs baseline: 1.0362x; 1.0006x over previous
; template <int DIR> __device__ __forceinline__ void lru_dir(const Params& p, int l, int n, int h, int lane, LAS bf16_t* XC, LAS float* STA, LAS float* STU) {
;     ...
;     for (int nf = 0; nf < 4; ++nf) {
; #pragma unroll
;         for (int ks = 0; ks < 2; ++ks) { wa[nf][ks] = *(const bf16x8*)(LWa + nf * 1024 + 32 * ks); wx[nf][ks] = *(const bf16x8*)(LWx + nf * 1024 + 32 * ks); }
;         const f32x4 lam4 = *(const f32x4*)(lam + 16 * nf + 4 * q); ba4[nf] = *(const f32x4*)(b_a + 16 * nf + 4 * q); bx4[nf] = *(const f32x4*)(b_x + 16 * nf + 4 * q);
; #pragma unroll
;         for (int r = 0; r < 4; ++r) { const float e = __expf(-lam4[r]); const float l1p = e < 0.05f ? e * (1.0f - e * (0.5f - e * (0.33333334f - e * 0.25f))) : __logf(1.0f + e); sp4[nf][r] = -8.0f * l1p; }
;     }
.LBB0_238:
	s_andn2_saveexec_b64 s[0:1], s[30:31]
	v_fmamk_f32 v73, v72, 0xbe800000, v226
	v_fma_f32 v73, -v72, v73, 0.5
	v_fma_f32 v73, -v72, v73, 1.0
	v_mul_f32_e32 v117, v72, v73
	s_or_b64 exec, exec, s[0:1]
	v_add_co_u32_e32 v80, vcc, 0x1000, v80
	s_nop 1
	v_addc_co_u32_e32 v81, vcc, 0, v81, vcc
	v_add_co_u32_e32 v84, vcc, 0x1000, v78
	s_nop 1
	v_addc_co_u32_e32 v85, vcc, 0, v79, vcc
	global_load_dwordx4 v[72:75], v[80:81], off offset:2048
	s_nop 0
	global_load_dwordx4 v[76:79], v[80:81], off offset:2112
	s_nop 0
	global_load_dwordx4 v[80:83], v[84:85], off offset:2048
	s_nop 0
	global_load_dwordx4 v[84:87], v[84:85], off offset:2112
	s_nop 0
	global_load_dwordx4 v[88:91], v[88:89], off offset:192
	s_nop 0
	global_load_dwordx4 v[92:95], v[92:93], off offset:192
	s_waitcnt vmcnt(6)
	v_mul_f32_e32 v96, 0xbfb8aa3b, v204
	v_exp_f32_e32 v118, v96
	s_nop 0
	v_cmp_ngt_f32_e32 vcc, s6, v118
	s_and_saveexec_b64 s[0:1], vcc
	s_xor_b64 s[30:31], exec, s[0:1]
	s_cbranch_execz .LBB0_242
	v_add_f32_e32 v96, 1.0, v118
	v_cmp_gt_f32_e32 vcc, s25, v96
	s_nop 1
	v_cndmask_b32_e64 v118, 0, 32, vcc
	v_ldexp_f32 v96, v96, v118
	v_log_f32_e32 v96, v96
	s_nop 0
	v_mul_f32_e32 v118, 0x3f317217, v96
	v_fma_f32 v118, v96, s36, -v118
	v_fmac_f32_e32 v118, 0x3377d1cf, v96
	v_fmac_f32_e32 v118, 0x3f317217, v96
	v_cmp_lt_f32_e64 s[0:1], |v96|, s37
	s_nop 1
	v_cndmask_b32_e64 v96, v96, v118, s[0:1]
	v_cndmask_b32_e32 v118, 0, v232, vcc
	v_sub_f32_e32 v96, v96, v118

; #define LAS __attribute__((address_space(3)))
; __device__ __forceinline__ float bf2f(bf16_t b) { return __uint_as_float(((unsigned)b) << 16); }
; __device__ __forceinline__ float sigmoidf_(float x) { return __builtin_amdgcn_rcpf(1.0f + __expf(-x)); }
; __device__ __forceinline__ f32x4 mfma16(bf16x8 a, bf16x8 b, f32x4 c) { return __builtin_amdgcn_mfma_f32_16x16x32_bf16(a, b, c, 0, 0, 0); }
; template <int DIR> __device__ __forceinline__ void lru_dir(const Params& p, int l, int n, int h, int lane, LAS bf16_t* XC, LAS float* STA, LAS float* STU) {
;     ...
;         bf16x8 xf[2];
; #pragma unroll
;         for (int ks = 0; ks < 2; ++ks) xf[ks] = *(const LAS bf16x8*)(XC + (16 * mi + c) * 520 + 64 * h + 32 * ks + 8 * q);
;         f32x4 za[4], zx[4];
; #pragma unroll
;         for (int nf = 0; nf < 4; ++nf) { za[nf] = (f32x4){0.f, 0.f, 0.f, 0.f}; zx[nf] = za[nf];
;             za[nf] = mfma16(wa[nf][0], xf[0], za[nf]); za[nf] = mfma16(wa[nf][1], xf[1], za[nf]);
;             zx[nf] = mfma16(wx[nf][0], xf[0], zx[nf]); zx[nf] = mfma16(wx[nf][1], xf[1], zx[nf]); }
; #pragma unroll
;         for (int nf = 0; nf < 4; ++nf) {
;             const int jo = 16 * nf + 4 * q;
;             const bf16x4 xc4 = *(const LAS bf16x4*)(XC + (16 * mi + c) * 520 + 64 * h + jo);
;             const f32x4 zav = za[nf] + ba4[nf], zxv = zx[nf] + bx4[nf];
;             f32x4 av, uv;
; #pragma unroll
;             for (int r = 0; r < 4; ++r) {
;                 const float ra = sigmoidf_(zav[r]), ix = sigmoidf_(zxv[r]);
;                 const float la = ra * sp4[nf][r];
;                 av[r] = __expf(la);
;                 const float x2 = 2.0f * la;
;                 const float om = -x2 * (1.0f + x2 * (0.5f + x2 * (0.16666667f + x2 * (0.041666668f + x2 * (0.0083333338f + x2 * (0.0013888889f + x2 * 0.0001984127f))))));
;                 uv[r] = bf2f((bf16_t)xc4[r]) * ix * __builtin_amdgcn_sqrtf(fmaxf(om, 0.f));
;             }
;             *(LAS f32x4*)(STA + c * 68 + jo) = av; *(LAS f32x4*)(STU + c * 68 + jo) = uv;
.Llru0_loop:
	ds_read_b128 v[172:175], v150
	ds_read_b128 v[178:181], v150 offset:64
	ds_read_b64 v[182:183], v151
	ds_read_b64 v[184:185], v151 offset:32
	ds_read_b64 v[186:187], v151 offset:64
	ds_read_b64 v[188:189], v151 offset:96
	s_add_u32 s64, s66, s0
	s_addc_u32 s65, s67, 0
	s_waitcnt lgkmcnt(4)
	v_mfma_f32_16x16x32_bf16 v[156:159], v[4:7], v[172:175], 0
	v_mfma_f32_16x16x32_bf16 v[96:99], v[0:3], v[172:175], 0
	v_mfma_f32_16x16x32_bf16 v[160:163], v[24:27], v[172:175], 0
	v_mfma_f32_16x16x32_bf16 v[100:103], v[32:35], v[172:175], 0
	v_mfma_f32_16x16x32_bf16 v[164:167], v[48:51], v[172:175], 0
	v_mfma_f32_16x16x32_bf16 v[104:107], v[56:59], v[172:175], 0
	v_mfma_f32_16x16x32_bf16 v[168:171], v[72:75], v[172:175], 0
	v_mfma_f32_16x16x32_bf16 v[108:111], v[80:83], v[172:175], 0
	v_mfma_f32_16x16x32_bf16 v[156:159], v[8:11], v[178:181], v[156:159]
	v_mfma_f32_16x16x32_bf16 v[96:99], v[12:15], v[178:181], v[96:99]
	v_mfma_f32_16x16x32_bf16 v[160:163], v[28:31], v[178:181], v[160:163]
	v_mfma_f32_16x16x32_bf16 v[100:103], v[36:39], v[178:181], v[100:103]
	v_mfma_f32_16x16x32_bf16 v[164:167], v[52:55], v[178:181], v[164:167]
	v_mfma_f32_16x16x32_bf16 v[104:107], v[60:63], v[178:181], v[104:107]
	v_mfma_f32_16x16x32_bf16 v[168:171], v[76:79], v[178:181], v[168:171]
	v_mfma_f32_16x16x32_bf16 v[108:111], v[84:87], v[178:181], v[108:111]
	s_waitcnt lgkmcnt(0)
	v_lshlrev_b32_e32 v204, 16, v182
	v_and_b32_e32 v205, 0xffff0000, v182
	v_lshlrev_b32_e32 v206, 16, v183
	v_and_b32_e32 v207, 0xffff0000, v183
	v_lshlrev_b32_e32 v208, 16, v184
	v_and_b32_e32 v209, 0xffff0000, v184
	v_lshlrev_b32_e32 v210, 16, v185
	v_and_b32_e32 v211, 0xffff0000, v185
	v_lshlrev_b32_e32 v212, 16, v186
	v_and_b32_e32 v213, 0xffff0000, v186
	v_lshlrev_b32_e32 v214, 16, v187
	v_and_b32_e32 v215, 0xffff0000, v187
	v_lshlrev_b32_e32 v216, 16, v188
	v_and_b32_e32 v217, 0xffff0000, v188
	v_lshlrev_b32_e32 v218, 16, v189
	v_and_b32_e32 v219, 0xffff0000, v189
	v_add_f32_e32 v192, v16, v156
	v_add_f32_e32 v195, v17, v157
	v_add_f32_e32 v198, v18, v158
	v_add_f32_e32 v201, v19, v159
	v_add_f32_e32 v193, v20, v96
	v_add_f32_e32 v196, v21, v97
	v_add_f32_e32 v199, v22, v98
	v_add_f32_e32 v202, v23, v99
	v_mul_f32_e32 v192, 0xbfb8aa3b, v192
	v_mul_f32_e32 v195, 0xbfb8aa3b, v195
	v_mul_f32_e32 v198, 0xbfb8aa3b, v198
	v_mul_f32_e32 v201, 0xbfb8aa3b, v201
	v_mul_f32_e32 v193, 0xbfb8aa3b, v193
	v_mul_f32_e32 v196, 0xbfb8aa3b, v196
	v_mul_f32_e32 v199, 0xbfb8aa3b, v199
	v_mul_f32_e32 v202, 0xbfb8aa3b, v202
	v_exp_f32_e32 v192, v192
	v_exp_f32_e32 v195, v195
	v_exp_f32_e32 v198, v198
	v_exp_f32_e32 v201, v201
	v_exp_f32_e32 v193, v193
	v_exp_f32_e32 v196, v196
	v_exp_f32_e32 v199, v199
	v_exp_f32_e32 v202, v202
	v_add_f32_e32 v192, 1.0, v192
	v_add_f32_e32 v195, 1.0, v195
	v_add_f32_e32 v198, 1.0, v198
	v_add_f32_e32 v201, 1.0, v201
	v_add_f32_e32 v193, 1.0, v193
	v_add_f32_e32 v196, 1.0, v196
	v_add_f32_e32 v199, 1.0, v199
	v_add_f32_e32 v202, 1.0, v202
	v_rcp_f32_e32 v192, v192
	v_rcp_f32_e32 v195, v195
	v_rcp_f32_e32 v198, v198
	v_rcp_f32_e32 v201, v201
	v_rcp_f32_e32 v193, v193
	v_rcp_f32_e32 v196, v196
	v_rcp_f32_e32 v199, v199
	v_rcp_f32_e32 v202, v202
	v_mul_f32_e32 v192, v148, v192
	v_mul_f32_e32 v195, v147, v195
	v_mul_f32_e32 v198, v146, v198
	v_mul_f32_e32 v201, v145, v201
	v_mul_f32_e32 v194, 0x3fb8aa3b, v192
	v_mul_f32_e32 v197, 0x3fb8aa3b, v195
	v_mul_f32_e32 v200, 0x3fb8aa3b, v198
	v_mul_f32_e32 v203, 0x3fb8aa3b, v201
	v_add_f32_e32 v192, v192, v192
	v_add_f32_e32 v195, v195, v195
	v_add_f32_e32 v198, v198, v198
	v_add_f32_e32 v201, v201, v201
	v_exp_f32_e32 v156, v194
	v_exp_f32_e32 v157, v197
	v_exp_f32_e32 v158, v200
	v_exp_f32_e32 v159, v203
	v_fmamk_f32 v194, v192, 0x39500d01, v227
	v_fmamk_f32 v197, v195, 0x39500d01, v227
	v_fmamk_f32 v200, v198, 0x39500d01, v227
	v_fmamk_f32 v203, v201, 0x39500d01, v227
	v_fmaak_f32 v194, v192, v194, 0x3c088889
	v_fmaak_f32 v197, v195, v197, 0x3c088889
	v_fmaak_f32 v200, v198, v200, 0x3c088889
	v_fmaak_f32 v203, v201, v203, 0x3c088889
	v_fmaak_f32 v194, v192, v194, 0x3d2aaaab
	v_fmaak_f32 v197, v195, v197, 0x3d2aaaab
	v_fmaak_f32 v200, v198, v200, 0x3d2aaaab
	v_fmaak_f32 v203, v201, v203, 0x3d2aaaab
	v_fmaak_f32 v194, v192, v194, 0x3e2aaaab
	v_fmaak_f32 v197, v195, v197, 0x3e2aaaab
	v_fmaak_f32 v200, v198, v200, 0x3e2aaaab
	v_fmaak_f32 v203, v201, v203, 0x3e2aaaab
	v_fma_f32 v194, v192, v194, 0.5
	v_fma_f32 v197, v195, v197, 0.5
	v_fma_f32 v200, v198, v200, 0.5
	v_fma_f32 v203, v201, v203, 0.5
	v_fma_f32 v194, v192, v194, 1.0
	v_fma_f32 v197, v195, v197, 1.0
	v_fma_f32 v200, v198, v200, 1.0
	v_fma_f32 v203, v201, v203, 1.0
	v_mul_f32_e64 v192, v194, -v192
	v_mul_f32_e64 v195, v197, -v195
	v_mul_f32_e64 v198, v200, -v198
	v_mul_f32_e64 v201, v203, -v201
	v_max_f32_e32 v192, 0, v192
	v_max_f32_e32 v195, 0, v195
	v_max_f32_e32 v198, 0, v198
	v_max_f32_e32 v201, 0, v201
	v_sqrt_f32_e32 v192, v192
	v_sqrt_f32_e32 v195, v195
	v_sqrt_f32_e32 v198, v198
	v_sqrt_f32_e32 v201, v201
	v_mul_f32_e32 v193, v193, v204
	v_mul_f32_e32 v196, v196, v205
	v_mul_f32_e32 v199, v199, v206
	v_mul_f32_e32 v202, v202, v207
	v_mul_f32_e32 v96, v193, v192
	v_mul_f32_e32 v97, v196, v195
	v_mul_f32_e32 v98, v199, v198
	v_mul_f32_e32 v99, v202, v201
	ds_write_b128 v154, v[156:159]
	ds_write_b128 v154, v[96:99] offset:4352
	v_add_f32_e32 v192, v40, v160
	v_add_f32_e32 v195, v41, v161
	v_add_f32_e32 v198, v42, v162
	v_add_f32_e32 v201, v43, v163
	v_add_f32_e32 v193, v44, v100
	v_add_f32_e32 v196, v45, v101
	v_add_f32_e32 v199, v46, v102
	v_add_f32_e32 v202, v47, v103
	v_mul_f32_e32 v192, 0xbfb8aa3b, v192
	v_mul_f32_e32 v195, 0xbfb8aa3b, v195
; #define LAS __attribute__((address_space(3)))
; __device__ __forceinline__ float bf2f(bf16_t b) { return __uint_as_float(((unsigned)b) << 16); }
; __device__ __forceinline__ float sigmoidf_(float x) { return __builtin_amdgcn_rcpf(1.0f + __expf(-x)); }
; template <int DIR> __device__ __forceinline__ void lru_dir(const Params& p, int l, int n, int h, int lane, LAS bf16_t* XC, LAS float* STA, LAS float* STU) {
;     ...
; #pragma unroll
;         for (int nf = 0; nf < 4; ++nf) {
;             const int jo = 16 * nf + 4 * q;
;             const bf16x4 xc4 = *(const LAS bf16x4*)(XC + (16 * mi + c) * 520 + 64 * h + jo);
;             const f32x4 zav = za[nf] + ba4[nf], zxv = zx[nf] + bx4[nf];
;             f32x4 av, uv;
; #pragma unroll
;             for (int r = 0; r < 4; ++r) {
;                 const float ra = sigmoidf_(zav[r]), ix = sigmoidf_(zxv[r]);
;                 const float la = ra * sp4[nf][r];
;                 av[r] = __expf(la);
;                 const float x2 = 2.0f * la;
;                 const float om = -x2 * (1.0f + x2 * (0.5f + x2 * (0.16666667f + x2 * (0.041666668f + x2 * (0.0083333338f + x2 * (0.0013888889f + x2 * 0.0001984127f))))));
;                 uv[r] = bf2f((bf16_t)xc4[r]) * ix * __builtin_amdgcn_sqrtf(fmaxf(om, 0.f));
;             }
;             *(LAS f32x4*)(STA + c * 68 + jo) = av; *(LAS f32x4*)(STU + c * 68 + jo) = uv;
	v_mul_f32_e32 v198, 0xbfb8aa3b, v198
	v_mul_f32_e32 v201, 0xbfb8aa3b, v201
	v_mul_f32_e32 v193, 0xbfb8aa3b, v193
	v_mul_f32_e32 v196, 0xbfb8aa3b, v196
	v_mul_f32_e32 v199, 0xbfb8aa3b, v199
	v_mul_f32_e32 v202, 0xbfb8aa3b, v202
	v_exp_f32_e32 v192, v192
	v_exp_f32_e32 v195, v195
	v_exp_f32_e32 v198, v198
	v_exp_f32_e32 v201, v201
	v_exp_f32_e32 v193, v193
	v_exp_f32_e32 v196, v196
	v_exp_f32_e32 v199, v199
	v_exp_f32_e32 v202, v202
	v_add_f32_e32 v192, 1.0, v192
	v_add_f32_e32 v195, 1.0, v195
	v_add_f32_e32 v198, 1.0, v198
	v_add_f32_e32 v201, 1.0, v201
	v_add_f32_e32 v193, 1.0, v193
	v_add_f32_e32 v196, 1.0, v196
	v_add_f32_e32 v199, 1.0, v199
	v_add_f32_e32 v202, 1.0, v202
	v_rcp_f32_e32 v192, v192
	v_rcp_f32_e32 v195, v195
	v_rcp_f32_e32 v198, v198
	v_rcp_f32_e32 v201, v201
	v_rcp_f32_e32 v193, v193
	v_rcp_f32_e32 v196, v196
	v_rcp_f32_e32 v199, v199
	v_rcp_f32_e32 v202, v202
	v_mul_f32_e32 v192, v144, v192
	v_mul_f32_e32 v195, v143, v195
	v_mul_f32_e32 v198, v142, v198
	v_mul_f32_e32 v201, v141, v201
	v_mul_f32_e32 v194, 0x3fb8aa3b, v192
	v_mul_f32_e32 v197, 0x3fb8aa3b, v195
	v_mul_f32_e32 v200, 0x3fb8aa3b, v198
	v_mul_f32_e32 v203, 0x3fb8aa3b, v201
	v_add_f32_e32 v192, v192, v192
	v_add_f32_e32 v195, v195, v195
	v_add_f32_e32 v198, v198, v198
	v_add_f32_e32 v201, v201, v201
	v_exp_f32_e32 v160, v194
	v_exp_f32_e32 v161, v197
	v_exp_f32_e32 v162, v200
	v_exp_f32_e32 v163, v203
	v_fmamk_f32 v194, v192, 0x39500d01, v227
	v_fmamk_f32 v197, v195, 0x39500d01, v227
	v_fmamk_f32 v200, v198, 0x39500d01, v227
	v_fmamk_f32 v203, v201, 0x39500d01, v227
	v_fmaak_f32 v194, v192, v194, 0x3c088889
	v_fmaak_f32 v197, v195, v197, 0x3c088889
	v_fmaak_f32 v200, v198, v200, 0x3c088889
	v_fmaak_f32 v203, v201, v203, 0x3c088889
	v_fmaak_f32 v194, v192, v194, 0x3d2aaaab
	v_fmaak_f32 v197, v195, v197, 0x3d2aaaab
	v_fmaak_f32 v200, v198, v200, 0x3d2aaaab
	v_fmaak_f32 v203, v201, v203, 0x3d2aaaab
	v_fmaak_f32 v194, v192, v194, 0x3e2aaaab
	v_fmaak_f32 v197, v195, v197, 0x3e2aaaab
	v_fmaak_f32 v200, v198, v200, 0x3e2aaaab
	v_fmaak_f32 v203, v201, v203, 0x3e2aaaab
	v_fma_f32 v194, v192, v194, 0.5
	v_fma_f32 v197, v195, v197, 0.5
	v_fma_f32 v200, v198, v200, 0.5
	v_fma_f32 v203, v201, v203, 0.5
	v_fma_f32 v194, v192, v194, 1.0
	v_fma_f32 v197, v195, v197, 1.0
	v_fma_f32 v200, v198, v200, 1.0
	v_fma_f32 v203, v201, v203, 1.0
	v_mul_f32_e64 v192, v194, -v192
	v_mul_f32_e64 v195, v197, -v195
	v_mul_f32_e64 v198, v200, -v198
	v_mul_f32_e64 v201, v203, -v201
	v_max_f32_e32 v192, 0, v192
	v_max_f32_e32 v195, 0, v195
	v_max_f32_e32 v198, 0, v198
	v_max_f32_e32 v201, 0, v201
	v_sqrt_f32_e32 v192, v192
	v_sqrt_f32_e32 v195, v195
	v_sqrt_f32_e32 v198, v198
	v_sqrt_f32_e32 v201, v201
	v_mul_f32_e32 v193, v193, v208
	v_mul_f32_e32 v196, v196, v209
	v_mul_f32_e32 v199, v199, v210
	v_mul_f32_e32 v202, v202, v211
	v_mul_f32_e32 v100, v193, v192
	v_mul_f32_e32 v101, v196, v195
	v_mul_f32_e32 v102, v199, v198
	v_mul_f32_e32 v103, v202, v201
	ds_write_b128 v154, v[160:163] offset:64
	ds_write_b128 v154, v[100:103] offset:4416
	v_add_f32_e32 v192, v64, v164
	v_add_f32_e32 v195, v65, v165
	v_add_f32_e32 v198, v66, v166
	v_add_f32_e32 v201, v67, v167
	v_add_f32_e32 v193, v68, v104
	v_add_f32_e32 v196, v69, v105
	v_add_f32_e32 v199, v70, v106
	v_add_f32_e32 v202, v71, v107
	v_mul_f32_e32 v192, 0xbfb8aa3b, v192
	v_mul_f32_e32 v195, 0xbfb8aa3b, v195
	v_mul_f32_e32 v198, 0xbfb8aa3b, v198
	v_mul_f32_e32 v201, 0xbfb8aa3b, v201
	v_mul_f32_e32 v193, 0xbfb8aa3b, v193
	v_mul_f32_e32 v196, 0xbfb8aa3b, v196
	v_mul_f32_e32 v199, 0xbfb8aa3b, v199
	v_mul_f32_e32 v202, 0xbfb8aa3b, v202
	v_exp_f32_e32 v192, v192
	v_exp_f32_e32 v195, v195
	v_exp_f32_e32 v198, v198
	v_exp_f32_e32 v201, v201
	v_exp_f32_e32 v193, v193
	v_exp_f32_e32 v196, v196
	v_exp_f32_e32 v199, v199
	v_exp_f32_e32 v202, v202
	v_add_f32_e32 v192, 1.0, v192
	v_add_f32_e32 v195, 1.0, v195
	v_add_f32_e32 v198, 1.0, v198
	v_add_f32_e32 v201, 1.0, v201
	v_add_f32_e32 v193, 1.0, v193
	v_add_f32_e32 v196, 1.0, v196
	v_add_f32_e32 v199, 1.0, v199
	v_add_f32_e32 v202, 1.0, v202
	v_rcp_f32_e32 v192, v192
	v_rcp_f32_e32 v195, v195
	v_rcp_f32_e32 v198, v198
	v_rcp_f32_e32 v201, v201
	v_rcp_f32_e32 v193, v193
	v_rcp_f32_e32 v196, v196
	v_rcp_f32_e32 v199, v199
	v_rcp_f32_e32 v202, v202
	v_mul_f32_e32 v192, v140, v192
	v_mul_f32_e32 v195, v139, v195
	v_mul_f32_e32 v198, v138, v198
	v_mul_f32_e32 v201, v137, v201
	v_mul_f32_e32 v194, 0x3fb8aa3b, v192
	v_mul_f32_e32 v197, 0x3fb8aa3b, v195
	v_mul_f32_e32 v200, 0x3fb8aa3b, v198
	v_mul_f32_e32 v203, 0x3fb8aa3b, v201
	v_add_f32_e32 v192, v192, v192
	v_add_f32_e32 v195, v195, v195
	v_add_f32_e32 v198, v198, v198
	v_add_f32_e32 v201, v201, v201
	v_exp_f32_e32 v164, v194
	v_exp_f32_e32 v165, v197
	v_exp_f32_e32 v166, v200
	v_exp_f32_e32 v167, v203
	v_fmamk_f32 v194, v192, 0x39500d01, v227
	v_fmamk_f32 v197, v195, 0x39500d01, v227
	v_fmamk_f32 v200, v198, 0x39500d01, v227
	v_fmamk_f32 v203, v201, 0x39500d01, v227
	v_fmaak_f32 v194, v192, v194, 0x3c088889
	v_fmaak_f32 v197, v195, v197, 0x3c088889
	v_fmaak_f32 v200, v198, v200, 0x3c088889
	v_fmaak_f32 v203, v201, v203, 0x3c088889
	v_fmaak_f32 v194, v192, v194, 0x3d2aaaab
	v_fmaak_f32 v197, v195, v197, 0x3d2aaaab
	v_fmaak_f32 v200, v198, v200, 0x3d2aaaab
	v_fmaak_f32 v203, v201, v203, 0x3d2aaaab
	v_fmaak_f32 v194, v192, v194, 0x3e2aaaab
	v_fmaak_f32 v197, v195, v197, 0x3e2aaaab
	v_fmaak_f32 v200, v198, v200, 0x3e2aaaab
	v_fmaak_f32 v203, v201, v203, 0x3e2aaaab
	v_fma_f32 v194, v192, v194, 0.5
	v_fma_f32 v197, v195, v197, 0.5
	v_fma_f32 v200, v198, v200, 0.5
	v_fma_f32 v203, v201, v203, 0.5
	v_fma_f32 v194, v192, v194, 1.0
	v_fma_f32 v197, v195, v197, 1.0
; #define LAS __attribute__((address_space(3)))
; __device__ __forceinline__ float bf2f(bf16_t b) { return __uint_as_float(((unsigned)b) << 16); }
; __device__ __forceinline__ unsigned cvtpk(float lo, float hi) { const f32x2 v = (f32x2){lo, hi}; const bf16v2 b = __builtin_convertvector(v, bf16v2); return __builtin_bit_cast(unsigned, b); }
; __device__ __forceinline__ float sigmoidf_(float x) { return __builtin_amdgcn_rcpf(1.0f + __expf(-x)); }
; template <int DIR> __device__ __forceinline__ void lru_dir(const Params& p, int l, int n, int h, int lane, LAS bf16_t* XC, LAS float* STA, LAS float* STU) {
;     ...
; #pragma unroll
;         for (int nf = 0; nf < 4; ++nf) {
;             const int jo = 16 * nf + 4 * q;
;             const bf16x4 xc4 = *(const LAS bf16x4*)(XC + (16 * mi + c) * 520 + 64 * h + jo);
;             const f32x4 zav = za[nf] + ba4[nf], zxv = zx[nf] + bx4[nf];
;             f32x4 av, uv;
; #pragma unroll
;             for (int r = 0; r < 4; ++r) {
;                 const float ra = sigmoidf_(zav[r]), ix = sigmoidf_(zxv[r]);
;                 const float la = ra * sp4[nf][r];
;                 av[r] = __expf(la);
;                 const float x2 = 2.0f * la;
;                 const float om = -x2 * (1.0f + x2 * (0.5f + x2 * (0.16666667f + x2 * (0.041666668f + x2 * (0.0083333338f + x2 * (0.0013888889f + x2 * 0.0001984127f))))));
;                 uv[r] = bf2f((bf16_t)xc4[r]) * ix * __builtin_amdgcn_sqrtf(fmaxf(om, 0.f));
;             }
;             *(LAS f32x4*)(STA + c * 68 + jo) = av; *(LAS f32x4*)(STU + c * 68 + jo) = uv;
;         }
;         LDS_FENCE();
;         float aa[16], uu[16];
; #pragma unroll
;         for (int s = 0; s < 16; ++s) { aa[s] = STA[s * 68 + j]; uu[s] = STU[s * 68 + j]; }
;         LDS_FENCE();
; #pragma unroll
;         for (int s = 0; s < 16; ++s) {
;             const int tl = DIR == 0 ? s : 15 - s;
;             hcar = aa[tl] * hcar + uu[tl]; P *= aa[tl];
;             const size_t row = (size_t)(t0 + 16 * mi + tl);
;             if (DIR == 0) { const unsigned w = cvtpk(hcar, P); y[row * D + 64 * h + j] = (bf16_t)(w & 0xffffu); y[row * D + 512 + 64 * h + j] = (bf16_t)(w >> 16); }
;             else { const unsigned w = cvtpk(bf2f(hfp[tl]) + hcar, P); y[row * D + 64 * h + j] = (bf16_t)(w & 0xffffu); __builtin_nontemporal_store((bf16_t)(w >> 16), PB + row * 512 + 64 * h + j); }
;         }
	v_fma_f32 v200, v198, v200, 1.0
	v_fma_f32 v203, v201, v203, 1.0
	v_mul_f32_e64 v192, v194, -v192
	v_mul_f32_e64 v195, v197, -v195
	v_mul_f32_e64 v198, v200, -v198
	v_mul_f32_e64 v201, v203, -v201
	v_max_f32_e32 v192, 0, v192
	v_max_f32_e32 v195, 0, v195
	v_max_f32_e32 v198, 0, v198
	v_max_f32_e32 v201, 0, v201
	v_sqrt_f32_e32 v192, v192
	v_sqrt_f32_e32 v195, v195
	v_sqrt_f32_e32 v198, v198
	v_sqrt_f32_e32 v201, v201
	v_mul_f32_e32 v193, v193, v212
	v_mul_f32_e32 v196, v196, v213
	v_mul_f32_e32 v199, v199, v214
	v_mul_f32_e32 v202, v202, v215
	v_mul_f32_e32 v104, v193, v192
	v_mul_f32_e32 v105, v196, v195
	v_mul_f32_e32 v106, v199, v198
	v_mul_f32_e32 v107, v202, v201
	ds_write_b128 v154, v[164:167] offset:128
	ds_write_b128 v154, v[104:107] offset:4480
	v_add_f32_e32 v192, v88, v168
	v_add_f32_e32 v195, v89, v169
	v_add_f32_e32 v198, v90, v170
	v_add_f32_e32 v201, v91, v171
	v_add_f32_e32 v193, v92, v108
	v_add_f32_e32 v196, v93, v109
	v_add_f32_e32 v199, v94, v110
	v_add_f32_e32 v202, v95, v111
	v_mul_f32_e32 v192, 0xbfb8aa3b, v192
	v_mul_f32_e32 v195, 0xbfb8aa3b, v195
	v_mul_f32_e32 v198, 0xbfb8aa3b, v198
	v_mul_f32_e32 v201, 0xbfb8aa3b, v201
	v_mul_f32_e32 v193, 0xbfb8aa3b, v193
	v_mul_f32_e32 v196, 0xbfb8aa3b, v196
	v_mul_f32_e32 v199, 0xbfb8aa3b, v199
	v_mul_f32_e32 v202, 0xbfb8aa3b, v202
	v_exp_f32_e32 v192, v192
	v_exp_f32_e32 v195, v195
	v_exp_f32_e32 v198, v198
	v_exp_f32_e32 v201, v201
	v_exp_f32_e32 v193, v193
	v_exp_f32_e32 v196, v196
	v_exp_f32_e32 v199, v199
	v_exp_f32_e32 v202, v202
	v_add_f32_e32 v192, 1.0, v192
	v_add_f32_e32 v195, 1.0, v195
	v_add_f32_e32 v198, 1.0, v198
	v_add_f32_e32 v201, 1.0, v201
	v_add_f32_e32 v193, 1.0, v193
	v_add_f32_e32 v196, 1.0, v196
	v_add_f32_e32 v199, 1.0, v199
	v_add_f32_e32 v202, 1.0, v202
	v_rcp_f32_e32 v192, v192
	v_rcp_f32_e32 v195, v195
	v_rcp_f32_e32 v198, v198
	v_rcp_f32_e32 v201, v201
	v_rcp_f32_e32 v193, v193
	v_rcp_f32_e32 v196, v196
	v_rcp_f32_e32 v199, v199
	v_rcp_f32_e32 v202, v202
	v_mul_f32_e32 v192, v136, v192
	v_mul_f32_e32 v195, v135, v195
	v_mul_f32_e32 v198, v134, v198
	v_mul_f32_e32 v201, v149, v201
	v_mul_f32_e32 v194, 0x3fb8aa3b, v192
	v_mul_f32_e32 v197, 0x3fb8aa3b, v195
	v_mul_f32_e32 v200, 0x3fb8aa3b, v198
	v_mul_f32_e32 v203, 0x3fb8aa3b, v201
	v_add_f32_e32 v192, v192, v192
	v_add_f32_e32 v195, v195, v195
	v_add_f32_e32 v198, v198, v198
	v_add_f32_e32 v201, v201, v201
	v_exp_f32_e32 v168, v194
	v_exp_f32_e32 v169, v197
	v_exp_f32_e32 v170, v200
	v_exp_f32_e32 v171, v203
	v_fmamk_f32 v194, v192, 0x39500d01, v227
	v_fmamk_f32 v197, v195, 0x39500d01, v227
	v_fmamk_f32 v200, v198, 0x39500d01, v227
	v_fmamk_f32 v203, v201, 0x39500d01, v227
	v_fmaak_f32 v194, v192, v194, 0x3c088889
	v_fmaak_f32 v197, v195, v197, 0x3c088889
	v_fmaak_f32 v200, v198, v200, 0x3c088889
	v_fmaak_f32 v203, v201, v203, 0x3c088889
	v_fmaak_f32 v194, v192, v194, 0x3d2aaaab
	v_fmaak_f32 v197, v195, v197, 0x3d2aaaab
	v_fmaak_f32 v200, v198, v200, 0x3d2aaaab
	v_fmaak_f32 v203, v201, v203, 0x3d2aaaab
	v_fmaak_f32 v194, v192, v194, 0x3e2aaaab
	v_fmaak_f32 v197, v195, v197, 0x3e2aaaab
	v_fmaak_f32 v200, v198, v200, 0x3e2aaaab
	v_fmaak_f32 v203, v201, v203, 0x3e2aaaab
	v_fma_f32 v194, v192, v194, 0.5
	v_fma_f32 v197, v195, v197, 0.5
	v_fma_f32 v200, v198, v200, 0.5
	v_fma_f32 v203, v201, v203, 0.5
	v_fma_f32 v194, v192, v194, 1.0
	v_fma_f32 v197, v195, v197, 1.0
	v_fma_f32 v200, v198, v200, 1.0
	v_fma_f32 v203, v201, v203, 1.0
	v_mul_f32_e64 v192, v194, -v192
	v_mul_f32_e64 v195, v197, -v195
	v_mul_f32_e64 v198, v200, -v198
	v_mul_f32_e64 v201, v203, -v201
	v_max_f32_e32 v192, 0, v192
	v_max_f32_e32 v195, 0, v195
	v_max_f32_e32 v198, 0, v198
	v_max_f32_e32 v201, 0, v201
	v_sqrt_f32_e32 v192, v192
	v_sqrt_f32_e32 v195, v195
	v_sqrt_f32_e32 v198, v198
	v_sqrt_f32_e32 v201, v201
	v_mul_f32_e32 v193, v193, v216
	v_mul_f32_e32 v196, v196, v217
	v_mul_f32_e32 v199, v199, v218
	v_mul_f32_e32 v202, v202, v219
	v_mul_f32_e32 v108, v193, v192
	v_mul_f32_e32 v109, v196, v195
	v_mul_f32_e32 v110, v199, v198
	v_mul_f32_e32 v111, v202, v201
	ds_write_b128 v154, v[168:171] offset:192
	ds_write_b128 v154, v[108:111] offset:4544
	s_waitcnt lgkmcnt(0)
	ds_read_b32 v204, v155
	ds_read_b32 v172, v155 offset:4352
	ds_read_b32 v205, v155 offset:272
	ds_read_b32 v173, v155 offset:4624
	ds_read_b32 v206, v155 offset:544
	ds_read_b32 v174, v155 offset:4896
	ds_read_b32 v207, v155 offset:816
	ds_read_b32 v175, v155 offset:5168
	ds_read_b32 v208, v155 offset:1088
	ds_read_b32 v178, v155 offset:5440
	ds_read_b32 v209, v155 offset:1360
	ds_read_b32 v179, v155 offset:5712
	ds_read_b32 v210, v155 offset:1632
	ds_read_b32 v180, v155 offset:5984
	ds_read_b32 v211, v155 offset:1904
	ds_read_b32 v181, v155 offset:6256
	s_waitcnt lgkmcnt(14)
	v_fma_f32 v130, v130, v204, v172
	v_mul_f32_e32 v129, v129, v204
	v_cvt_pk_bf16_f32 v190, v130, v129
	global_store_short v220, v190, s[64:65] offset:-4096
	global_store_short_d16_hi v220, v190, s[64:65] offset:-3072
	ds_read_b32 v212, v155 offset:2176
	ds_read_b32 v182, v155 offset:6528
	s_waitcnt lgkmcnt(14)
	v_fma_f32 v130, v130, v205, v173
	v_mul_f32_e32 v129, v129, v205
	v_cvt_pk_bf16_f32 v191, v130, v129
	global_store_short v220, v191, s[64:65] offset:-2048
	global_store_short_d16_hi v220, v191, s[64:65] offset:-1024
	ds_read_b32 v213, v155 offset:2448
	ds_read_b32 v183, v155 offset:6800
	s_waitcnt lgkmcnt(14)
	v_fma_f32 v130, v130, v206, v174
	v_mul_f32_e32 v129, v129, v206
	v_cvt_pk_bf16_f32 v190, v130, v129
	global_store_short v220, v190, s[64:65] offset:0
	global_store_short_d16_hi v220, v190, s[64:65] offset:1024
	ds_read_b32 v214, v155 offset:2720
	ds_read_b32 v184, v155 offset:7072
	s_waitcnt lgkmcnt(14)
; __device__ __forceinline__ float bf2f(bf16_t b) { return __uint_as_float(((unsigned)b) << 16); }
; __device__ __forceinline__ unsigned cvtpk(float lo, float hi) { const f32x2 v = (f32x2){lo, hi}; const bf16v2 b = __builtin_convertvector(v, bf16v2); return __builtin_bit_cast(unsigned, b); }
; template <int DIR> __device__ __forceinline__ void lru_dir(const Params& p, int l, int n, int h, int lane, LAS bf16_t* XC, LAS float* STA, LAS float* STU) {
;     ...
;     const float* lam = p.in[10] + (size_t)(l * 2 + DIR) * 512 + 64 * h; const float* b_a = p.in[7] + (size_t)(l * 2 + DIR) * 512 + 64 * h; const float* b_x = p.in[9] + (size_t)(l * 2 + DIR) * 512 + 64 * h;
;     const bf16_t* LWa = LW + ((size_t)(DIR * 2 + 0) * 8 + h) * 4096 + c * 64 + 8 * q; const bf16_t* LWx = LW + ((size_t)(DIR * 2 + 1) * 8 + h) * 4096 + c * 64 + 8 * q;
;     bf16x8 wa[4][2], wx[4][2]; f32x4 sp4[4], ba4[4], bx4[4];
; #pragma unroll
;     for (int nf = 0; nf < 4; ++nf) {
; #pragma unroll
;         for (int ks = 0; ks < 2; ++ks) { wa[nf][ks] = *(const bf16x8*)(LWa + nf * 1024 + 32 * ks); wx[nf][ks] = *(const bf16x8*)(LWx + nf * 1024 + 32 * ks); }
;         const f32x4 lam4 = *(const f32x4*)(lam + 16 * nf + 4 * q); ba4[nf] = *(const f32x4*)(b_a + 16 * nf + 4 * q); bx4[nf] = *(const f32x4*)(b_x + 16 * nf + 4 * q);
; #pragma unroll
;         for (int r = 0; r < 4; ++r) { const float e = __expf(-lam4[r]); const float l1p = e < 0.05f ? e * (1.0f - e * (0.5f - e * (0.33333334f - e * 0.25f))) : __logf(1.0f + e); sp4[nf][r] = -8.0f * l1p; }
;     ...
; #pragma unroll
;         for (int s = 0; s < 16; ++s) {
;             const int tl = DIR == 0 ? s : 15 - s;
;             hcar = aa[tl] * hcar + uu[tl]; P *= aa[tl];
;             const size_t row = (size_t)(t0 + 16 * mi + tl);
;             if (DIR == 0) { const unsigned w = cvtpk(hcar, P); y[row * D + 64 * h + j] = (bf16_t)(w & 0xffffu); y[row * D + 512 + 64 * h + j] = (bf16_t)(w >> 16); }
;             else { const unsigned w = cvtpk(bf2f(hfp[tl]) + hcar, P); y[row * D + 64 * h + j] = (bf16_t)(w & 0xffffu); __builtin_nontemporal_store((bf16_t)(w >> 16), PB + row * 512 + 64 * h + j); }
;         }
;     }
;     Aprod[(size_t)(DIR * NCH + n) * 512 + 64 * h + j] = P; Hend[(size_t)(DIR * NCH + n) * 512 + 64 * h + j] = hcar;
	v_fma_f32 v130, v130, v207, v175
	v_mul_f32_e32 v129, v129, v207
	v_cvt_pk_bf16_f32 v191, v130, v129
	global_store_short v220, v191, s[64:65] offset:2048
	global_store_short_d16_hi v220, v191, s[64:65] offset:3072
	ds_read_b32 v215, v155 offset:2992
	ds_read_b32 v185, v155 offset:7344
	s_waitcnt lgkmcnt(14)
	v_fma_f32 v130, v130, v208, v178
	v_mul_f32_e32 v129, v129, v208
	v_cvt_pk_bf16_f32 v190, v130, v129
	s_add_u32 s64, s64, 0x2000
	s_addc_u32 s65, s65, 0
	global_store_short v220, v190, s[64:65] offset:-4096
	global_store_short_d16_hi v220, v190, s[64:65] offset:-3072
	ds_read_b32 v216, v155 offset:3264
	ds_read_b32 v186, v155 offset:7616
	s_waitcnt lgkmcnt(14)
	v_fma_f32 v130, v130, v209, v179
	v_mul_f32_e32 v129, v129, v209
	v_cvt_pk_bf16_f32 v191, v130, v129
	global_store_short v220, v191, s[64:65] offset:-2048
	global_store_short_d16_hi v220, v191, s[64:65] offset:-1024
	ds_read_b32 v217, v155 offset:3536
	ds_read_b32 v187, v155 offset:7888
	s_waitcnt lgkmcnt(14)
	v_fma_f32 v130, v130, v210, v180
	v_mul_f32_e32 v129, v129, v210
	v_cvt_pk_bf16_f32 v190, v130, v129
	global_store_short v220, v190, s[64:65] offset:0
	global_store_short_d16_hi v220, v190, s[64:65] offset:1024
	ds_read_b32 v218, v155 offset:3808
	ds_read_b32 v188, v155 offset:8160
	s_waitcnt lgkmcnt(14)
	v_fma_f32 v130, v130, v211, v181
	v_mul_f32_e32 v129, v129, v211
	v_cvt_pk_bf16_f32 v191, v130, v129
	global_store_short v220, v191, s[64:65] offset:2048
	global_store_short_d16_hi v220, v191, s[64:65] offset:3072
	ds_read_b32 v219, v155 offset:4080
	ds_read_b32 v189, v155 offset:8432
	s_waitcnt lgkmcnt(14)
	v_fma_f32 v130, v130, v212, v182
	v_mul_f32_e32 v129, v129, v212
	v_cvt_pk_bf16_f32 v190, v130, v129
	s_add_u32 s64, s64, 0x2000
	s_addc_u32 s65, s65, 0
	global_store_short v220, v190, s[64:65] offset:-4096
	global_store_short_d16_hi v220, v190, s[64:65] offset:-3072
	s_waitcnt lgkmcnt(12)
	v_fma_f32 v130, v130, v213, v183
	v_mul_f32_e32 v129, v129, v213
	v_cvt_pk_bf16_f32 v191, v130, v129
	global_store_short v220, v191, s[64:65] offset:-2048
	global_store_short_d16_hi v220, v191, s[64:65] offset:-1024
	s_waitcnt lgkmcnt(10)
	v_fma_f32 v130, v130, v214, v184
	v_mul_f32_e32 v129, v129, v214
	v_cvt_pk_bf16_f32 v190, v130, v129
	global_store_short v220, v190, s[64:65] offset:0
	global_store_short_d16_hi v220, v190, s[64:65] offset:1024
	s_waitcnt lgkmcnt(8)
	v_fma_f32 v130, v130, v215, v185
	v_mul_f32_e32 v129, v129, v215
	v_cvt_pk_bf16_f32 v191, v130, v129
	global_store_short v220, v191, s[64:65] offset:2048
	global_store_short_d16_hi v220, v191, s[64:65] offset:3072
	s_waitcnt lgkmcnt(6)
	v_fma_f32 v130, v130, v216, v186
	v_mul_f32_e32 v129, v129, v216
	v_cvt_pk_bf16_f32 v190, v130, v129
	s_add_u32 s64, s64, 0x2000
	s_addc_u32 s65, s65, 0
	global_store_short v220, v190, s[64:65] offset:-4096
	global_store_short_d16_hi v220, v190, s[64:65] offset:-3072
	s_waitcnt lgkmcnt(4)
	v_fma_f32 v130, v130, v217, v187
	v_mul_f32_e32 v129, v129, v217
	v_cvt_pk_bf16_f32 v191, v130, v129
	global_store_short v220, v191, s[64:65] offset:-2048
	global_store_short_d16_hi v220, v191, s[64:65] offset:-1024
	s_waitcnt lgkmcnt(2)
	v_fma_f32 v130, v130, v218, v188
	v_mul_f32_e32 v129, v129, v218
	v_cvt_pk_bf16_f32 v190, v130, v129
	global_store_short v220, v190, s[64:65] offset:0
	global_store_short_d16_hi v220, v190, s[64:65] offset:1024
	s_waitcnt lgkmcnt(0)
	v_fma_f32 v130, v130, v219, v189
	v_mul_f32_e32 v129, v129, v219
	v_cvt_pk_bf16_f32 v191, v130, v129
	global_store_short v220, v191, s[64:65] offset:2048
	global_store_short_d16_hi v220, v191, s[64:65] offset:3072
	s_add_u32 s0, s0, 0x8000
	s_addc_u32 s1, s1, 0
	v_add_u32_e32 v150, 0x4100, v150
	v_add_u32_e32 v151, 0x4100, v151
	s_cmp_lg_u32 s0, 0x20000
	s_cbranch_scc1 .Llru0_loop
	v_add_u32_e32 v156, 0x1000, v155
	v_add_u32_e32 v157, 0x1200, v155
	v_add_u32_e32 v158, 0x400, v155
	v_add_u32_e32 v159, 0x1400, v155
	v_add_u32_e32 v160, 0x1600, v155
	v_add_u32_e32 v161, 0x800, v155
	v_add_u32_e32 v162, 0x1800, v155
	v_add_u32_e32 v163, 0x1a00, v155
	v_add_u32_e32 v164, 0xc00, v155
	v_add_u32_e32 v165, 0x1c00, v155
	v_add_u32_e32 v166, 0x1e00, v155
	s_ashr_i32 s5, s4, 31
	s_lshl_b64 s[0:1], s[4:5], 9
	v_lshl_add_u64 v[0:1], s[0:1], 0, v[124:125]
	v_or_b32_e32 v0, v0, v126
	v_readlane_b32 s0, v254, 11
	v_lshlrev_b64 v[0:1], 2, v[0:1]
	v_readlane_b32 s1, v254, 12
	v_lshlrev_b32_e32 v6, 1, v121
	v_mov_b32_e32 v7, v177
	v_lshl_add_u64 v[2:3], s[0:1], 0, v[0:1]
	v_readlane_b32 s0, v254, 13
	v_readlane_b32 s1, v254, 14
	v_lshlrev_b32_e32 v8, 1, v133
	v_mov_b32_e32 v9, v177
	v_lshl_add_u64 v[6:7], v[114:115], 0, v[6:7]
	v_lshl_add_u64 v[0:1], s[0:1], 0, v[0:1]
	v_lshl_add_u64 v[6:7], v[6:7], 0, v[8:9]
	s_mov_b64 s[0:1], 0x20000
	v_lshl_add_u64 v[80:81], v[6:7], 0, s[0:1]
	s_mov_b64 s[0:1], 0x30000
	global_store_dword v[0:1], v130, off
	v_lshl_add_u64 v[0:1], s[22:23], 0, v[112:113]
	v_lshl_add_u64 v[78:79], v[6:7], 0, s[0:1]
	v_mov_b32_e32 v121, v177
	s_mov_b32 s0, 0x20000
	v_lshl_add_u64 v[76:77], v[0:1], 0, v[120:121]
	v_add_co_u32_e32 v0, vcc, s0, v6
	v_lshl_add_u64 v[4:5], s[38:39], 0, v[112:113]
	s_nop 0
	v_addc_co_u32_e32 v1, vcc, 0, v7, vcc
	v_lshl_add_u64 v[92:93], v[4:5], 0, v[120:121]
	v_add_co_u32_e32 v4, vcc, 0x30000, v6
	global_store_dword v[2:3], v129, off
	v_lshl_add_u64 v[2:3], s[26:27], 0, v[112:113]
	v_addc_co_u32_e32 v5, vcc, 0, v7, vcc
	v_lshl_add_u64 v[88:89], v[2:3], 0, v[120:121]
	global_load_dwordx4 v[192:195], v[76:77], off
	global_load_dwordx4 v[196:199], v[76:77], off offset:64
	global_load_dwordx4 v[200:203], v[76:77], off offset:128
	global_load_dwordx4 v[204:207], v[76:77], off offset:192
	s_nop 0
	global_load_dwordx4 v[0:3], v[0:1], off
	s_nop 0
	global_load_dwordx4 v[4:7], v[4:5], off
	s_nop 0
	global_load_dwordx4 v[8:11], v[80:81], off offset:64
	global_load_dwordx4 v[12:15], v[78:79], off offset:64
	global_load_dwordx4 v[16:19], v[88:89], off
	global_load_dwordx4 v[20:23], v[92:93], off
	s_waitcnt vmcnt(6)
	v_mul_f32_e32 v24, 0xbfb8aa3b, v192
	v_exp_f32_e32 v24, v24
	s_nop 0
	v_cmp_ngt_f32_e32 vcc, s6, v24
	s_and_saveexec_b64 s[0:1], vcc
	s_xor_b64 s[30:31], exec, s[0:1]
	s_cbranch_execz .LBB0_260
	v_add_f32_e32 v24, 1.0, v24
	v_cmp_gt_f32_e32 vcc, s25, v24
	s_nop 1
	v_cndmask_b32_e64 v28, 0, 32, vcc
	v_ldexp_f32 v24, v24, v28
	v_log_f32_e32 v24, v24
	s_nop 0
	v_mul_f32_e32 v28, 0x3f317217, v24
	v_fma_f32 v28, v24, s36, -v28
	v_fmac_f32_e32 v28, 0x3377d1cf, v24
	v_fmac_f32_e32 v28, 0x3f317217, v24
	v_cmp_lt_f32_e64 s[0:1], |v24|, s37
	s_nop 1
	v_cndmask_b32_e64 v24, v24, v28, s[0:1]
	v_cndmask_b32_e32 v28, 0, v232, vcc
	v_sub_f32_e32 v100, v24, v28
; template <int DIR> __device__ __forceinline__ void lru_dir(const Params& p, int l, int n, int h, int lane, LAS bf16_t* XC, LAS float* STA, LAS float* STU) {
;     ...
;     for (int nf = 0; nf < 4; ++nf) {
; #pragma unroll
;         for (int ks = 0; ks < 2; ++ks) { wa[nf][ks] = *(const bf16x8*)(LWa + nf * 1024 + 32 * ks); wx[nf][ks] = *(const bf16x8*)(LWx + nf * 1024 + 32 * ks); }
;         const f32x4 lam4 = *(const f32x4*)(lam + 16 * nf + 4 * q); ba4[nf] = *(const f32x4*)(b_a + 16 * nf + 4 * q); bx4[nf] = *(const f32x4*)(b_x + 16 * nf + 4 * q);
; #pragma unroll
;         for (int r = 0; r < 4; ++r) { const float e = __expf(-lam4[r]); const float l1p = e < 0.05f ? e * (1.0f - e * (0.5f - e * (0.33333334f - e * 0.25f))) : __logf(1.0f + e); sp4[nf][r] = -8.0f * l1p; }
;     }
.LBB0_260:
	s_andn2_saveexec_b64 s[0:1], s[30:31]
	v_fmamk_f32 v28, v24, 0xbe800000, v226
	v_fma_f32 v28, -v24, v28, 0.5
	v_fma_f32 v28, -v24, v28, 1.0
	v_mul_f32_e32 v100, v24, v28
	s_or_b64 exec, exec, s[0:1]
	v_mul_f32_e32 v24, 0xbfb8aa3b, v193
	v_exp_f32_e32 v24, v24
	s_nop 0
	v_cmp_ngt_f32_e32 vcc, s6, v24
	s_and_saveexec_b64 s[0:1], vcc
	s_xor_b64 s[30:31], exec, s[0:1]
	s_cbranch_execz .LBB0_264
	v_add_f32_e32 v24, 1.0, v24
	v_cmp_gt_f32_e32 vcc, s25, v24
	s_nop 1
	v_cndmask_b32_e64 v25, 0, 32, vcc
	v_ldexp_f32 v24, v24, v25
	v_log_f32_e32 v24, v24
	s_nop 0
	v_mul_f32_e32 v25, 0x3f317217, v24
	v_fma_f32 v25, v24, s36, -v25
	v_fmac_f32_e32 v25, 0x3377d1cf, v24
	v_fmac_f32_e32 v25, 0x3f317217, v24
	v_cmp_lt_f32_e64 s[0:1], |v24|, s37
	s_nop 1
	v_cndmask_b32_e64 v24, v24, v25, s[0:1]
	v_cndmask_b32_e32 v25, 0, v232, vcc
	v_sub_f32_e32 v101, v24, v25
.LBB0_264:
	s_andn2_saveexec_b64 s[0:1], s[30:31]
	v_fmamk_f32 v25, v24, 0xbe800000, v226
	v_fma_f32 v25, -v24, v25, 0.5
	v_fma_f32 v25, -v24, v25, 1.0
	v_mul_f32_e32 v101, v24, v25
	s_or_b64 exec, exec, s[0:1]
	v_mul_f32_e32 v24, 0xbfb8aa3b, v194
	v_exp_f32_e32 v24, v24
	s_nop 0
	v_cmp_ngt_f32_e32 vcc, s6, v24
	s_and_saveexec_b64 s[0:1], vcc
	s_xor_b64 s[30:31], exec, s[0:1]
	s_cbranch_execz .LBB0_268
	v_add_f32_e32 v24, 1.0, v24
	v_cmp_gt_f32_e32 vcc, s25, v24
	s_nop 1
	v_cndmask_b32_e64 v25, 0, 32, vcc
	v_ldexp_f32 v24, v24, v25
	v_log_f32_e32 v24, v24
	s_nop 0
	v_mul_f32_e32 v25, 0x3f317217, v24
	v_fma_f32 v25, v24, s36, -v25
	v_fmac_f32_e32 v25, 0x3377d1cf, v24
	v_fmac_f32_e32 v25, 0x3f317217, v24
	v_cmp_lt_f32_e64 s[0:1], |v24|, s37
	s_nop 1
	v_cndmask_b32_e64 v24, v24, v25, s[0:1]
	v_cndmask_b32_e32 v25, 0, v232, vcc
	v_sub_f32_e32 v102, v24, v25
.LBB0_268:
	s_andn2_saveexec_b64 s[0:1], s[30:31]
	v_fmamk_f32 v25, v24, 0xbe800000, v226
	v_fma_f32 v25, -v24, v25, 0.5
	v_fma_f32 v25, -v24, v25, 1.0
	v_mul_f32_e32 v102, v24, v25
	s_or_b64 exec, exec, s[0:1]
	v_mul_f32_e32 v24, 0xbfb8aa3b, v195
	v_exp_f32_e32 v24, v24
	s_nop 0
	v_cmp_ngt_f32_e32 vcc, s6, v24
	s_and_saveexec_b64 s[0:1], vcc
	s_xor_b64 s[30:31], exec, s[0:1]
	s_cbranch_execz .LBB0_272
	v_add_f32_e32 v24, 1.0, v24
	v_cmp_gt_f32_e32 vcc, s25, v24
	s_nop 1
	v_cndmask_b32_e64 v25, 0, 32, vcc
	v_ldexp_f32 v24, v24, v25
	v_log_f32_e32 v24, v24
	s_nop 0
	v_mul_f32_e32 v25, 0x3f317217, v24
	v_fma_f32 v25, v24, s36, -v25
	v_fmac_f32_e32 v25, 0x3377d1cf, v24
	v_fmac_f32_e32 v25, 0x3f317217, v24
	v_cmp_lt_f32_e64 s[0:1], |v24|, s37
	s_nop 1
	v_cndmask_b32_e64 v24, v24, v25, s[0:1]
	v_cndmask_b32_e32 v25, 0, v232, vcc
	v_sub_f32_e32 v103, v24, v25
.LBB0_272:
	s_andn2_saveexec_b64 s[0:1], s[30:31]
	v_fmamk_f32 v25, v24, 0xbe800000, v226
	v_fma_f32 v25, -v24, v25, 0.5
	v_fma_f32 v25, -v24, v25, 1.0
	v_mul_f32_e32 v103, v24, v25
	s_or_b64 exec, exec, s[0:1]
	global_load_dwordx4 v[24:27], v[80:81], off offset:2048
	global_load_dwordx4 v[28:31], v[80:81], off offset:2112
	global_load_dwordx4 v[32:35], v[78:79], off offset:2048
	global_load_dwordx4 v[36:39], v[78:79], off offset:2112
	global_load_dwordx4 v[40:43], v[88:89], off offset:64
	global_load_dwordx4 v[44:47], v[92:93], off offset:64
	v_mul_f32_e32 v48, 0xbfb8aa3b, v196
	v_exp_f32_e32 v48, v48
	s_nop 0
	v_cmp_ngt_f32_e32 vcc, s6, v48
	s_and_saveexec_b64 s[0:1], vcc
	s_xor_b64 s[30:31], exec, s[0:1]
	s_cbranch_execz .LBB0_276
	v_add_f32_e32 v48, 1.0, v48
	v_cmp_gt_f32_e32 vcc, s25, v48
	s_nop 1
	v_cndmask_b32_e64 v52, 0, 32, vcc
	v_ldexp_f32 v48, v48, v52
	v_log_f32_e32 v48, v48
	s_nop 0
	v_mul_f32_e32 v52, 0x3f317217, v48
	v_fma_f32 v52, v48, s36, -v52
	v_fmac_f32_e32 v52, 0x3377d1cf, v48
	v_fmac_f32_e32 v52, 0x3f317217, v48
	v_cmp_lt_f32_e64 s[0:1], |v48|, s37
	s_nop 1
	v_cndmask_b32_e64 v48, v48, v52, s[0:1]
	v_cndmask_b32_e32 v52, 0, v232, vcc
	v_sub_f32_e32 v104, v48, v52
.LBB0_276:
	s_andn2_saveexec_b64 s[0:1], s[30:31]
	v_fmamk_f32 v52, v48, 0xbe800000, v226
	v_fma_f32 v52, -v48, v52, 0.5
	v_fma_f32 v52, -v48, v52, 1.0
	v_mul_f32_e32 v104, v48, v52
	s_or_b64 exec, exec, s[0:1]
	v_mul_f32_e32 v48, 0xbfb8aa3b, v197
	v_exp_f32_e32 v48, v48
	s_nop 0
	v_cmp_ngt_f32_e32 vcc, s6, v48
	s_and_saveexec_b64 s[0:1], vcc
	s_xor_b64 s[30:31], exec, s[0:1]
	s_cbranch_execz .LBB0_280
	v_add_f32_e32 v48, 1.0, v48
	v_cmp_gt_f32_e32 vcc, s25, v48
	s_nop 1
	v_cndmask_b32_e64 v49, 0, 32, vcc
	v_ldexp_f32 v48, v48, v49
	v_log_f32_e32 v48, v48
	s_nop 0
	v_mul_f32_e32 v49, 0x3f317217, v48
	v_fma_f32 v49, v48, s36, -v49
	v_fmac_f32_e32 v49, 0x3377d1cf, v48
	v_fmac_f32_e32 v49, 0x3f317217, v48
	v_cmp_lt_f32_e64 s[0:1], |v48|, s37
	s_nop 1
	v_cndmask_b32_e64 v48, v48, v49, s[0:1]
	v_cndmask_b32_e32 v49, 0, v232, vcc
	v_sub_f32_e32 v105, v48, v49
.LBB0_280:
	s_andn2_saveexec_b64 s[0:1], s[30:31]
	v_fmamk_f32 v49, v48, 0xbe800000, v226
	v_fma_f32 v49, -v48, v49, 0.5
	v_fma_f32 v49, -v48, v49, 1.0
	v_mul_f32_e32 v105, v48, v49
	s_or_b64 exec, exec, s[0:1]
	v_mul_f32_e32 v48, 0xbfb8aa3b, v198
	v_exp_f32_e32 v48, v48
	s_nop 0
	v_cmp_ngt_f32_e32 vcc, s6, v48
	s_and_saveexec_b64 s[0:1], vcc
	s_xor_b64 s[30:31], exec, s[0:1]
	s_cbranch_execz .LBB0_284
	v_add_f32_e32 v48, 1.0, v48
	v_cmp_gt_f32_e32 vcc, s25, v48
	s_nop 1
	v_cndmask_b32_e64 v49, 0, 32, vcc
	v_ldexp_f32 v48, v48, v49
	v_log_f32_e32 v48, v48
	s_nop 0
	v_mul_f32_e32 v49, 0x3f317217, v48
	v_fma_f32 v49, v48, s36, -v49
	v_fmac_f32_e32 v49, 0x3377d1cf, v48
	v_fmac_f32_e32 v49, 0x3f317217, v48
	v_cmp_lt_f32_e64 s[0:1], |v48|, s37
	s_nop 1
	v_cndmask_b32_e64 v48, v48, v49, s[0:1]
	v_cndmask_b32_e32 v49, 0, v232, vcc
	v_sub_f32_e32 v106, v48, v49
; template <int DIR> __device__ __forceinline__ void lru_dir(const Params& p, int l, int n, int h, int lane, LAS bf16_t* XC, LAS float* STA, LAS float* STU) {
;     ...
;     for (int nf = 0; nf < 4; ++nf) {
; #pragma unroll
;         for (int ks = 0; ks < 2; ++ks) { wa[nf][ks] = *(const bf16x8*)(LWa + nf * 1024 + 32 * ks); wx[nf][ks] = *(const bf16x8*)(LWx + nf * 1024 + 32 * ks); }
;         const f32x4 lam4 = *(const f32x4*)(lam + 16 * nf + 4 * q); ba4[nf] = *(const f32x4*)(b_a + 16 * nf + 4 * q); bx4[nf] = *(const f32x4*)(b_x + 16 * nf + 4 * q);
; #pragma unroll
;         for (int r = 0; r < 4; ++r) { const float e = __expf(-lam4[r]); const float l1p = e < 0.05f ? e * (1.0f - e * (0.5f - e * (0.33333334f - e * 0.25f))) : __logf(1.0f + e); sp4[nf][r] = -8.0f * l1p; }
;     }
.LBB0_284:
	s_andn2_saveexec_b64 s[0:1], s[30:31]
	v_fmamk_f32 v49, v48, 0xbe800000, v226
	v_fma_f32 v49, -v48, v49, 0.5
	v_fma_f32 v49, -v48, v49, 1.0
	v_mul_f32_e32 v106, v48, v49
	s_or_b64 exec, exec, s[0:1]
	v_mul_f32_e32 v48, 0xbfb8aa3b, v199
	v_exp_f32_e32 v48, v48
	s_nop 0
	v_cmp_ngt_f32_e32 vcc, s6, v48
	s_and_saveexec_b64 s[0:1], vcc
	s_xor_b64 s[30:31], exec, s[0:1]
	s_cbranch_execz .LBB0_288
	v_add_f32_e32 v48, 1.0, v48
	v_cmp_gt_f32_e32 vcc, s25, v48
	s_nop 1
	v_cndmask_b32_e64 v49, 0, 32, vcc
	v_ldexp_f32 v48, v48, v49
	v_log_f32_e32 v48, v48
	s_nop 0
	v_mul_f32_e32 v49, 0x3f317217, v48
	v_fma_f32 v49, v48, s36, -v49
	v_fmac_f32_e32 v49, 0x3377d1cf, v48
	v_fmac_f32_e32 v49, 0x3f317217, v48
	v_cmp_lt_f32_e64 s[0:1], |v48|, s37
	s_nop 1
	v_cndmask_b32_e64 v48, v48, v49, s[0:1]
	v_cndmask_b32_e32 v49, 0, v232, vcc
	v_sub_f32_e32 v107, v48, v49
.LBB0_288:
	s_andn2_saveexec_b64 s[0:1], s[30:31]
	v_fmamk_f32 v49, v48, 0xbe800000, v226
	v_fma_f32 v49, -v48, v49, 0.5
	v_fma_f32 v49, -v48, v49, 1.0
	v_mul_f32_e32 v107, v48, v49
	s_or_b64 exec, exec, s[0:1]
	v_add_co_u32_e32 v52, vcc, 0x1000, v80
	s_nop 1
	v_addc_co_u32_e32 v53, vcc, 0, v81, vcc
	v_add_co_u32_e32 v60, vcc, 0x1000, v78
	s_nop 1
	v_addc_co_u32_e32 v61, vcc, 0, v79, vcc
	global_load_dwordx4 v[48:51], v[52:53], off
	s_nop 0
	global_load_dwordx4 v[52:55], v[52:53], off offset:64
	s_nop 0
	global_load_dwordx4 v[56:59], v[60:61], off
	s_nop 0
	global_load_dwordx4 v[60:63], v[60:61], off offset:64
	s_nop 0
	global_load_dwordx4 v[64:67], v[88:89], off offset:128
	global_load_dwordx4 v[68:71], v[92:93], off offset:128
	v_mul_f32_e32 v72, 0xbfb8aa3b, v200
	v_exp_f32_e32 v72, v72
	s_nop 0
	v_cmp_ngt_f32_e32 vcc, s6, v72
	s_and_saveexec_b64 s[0:1], vcc
	s_xor_b64 s[30:31], exec, s[0:1]
	s_cbranch_execz .LBB0_292
	v_add_f32_e32 v72, 1.0, v72
	v_cmp_gt_f32_e32 vcc, s25, v72
	s_nop 1
	v_cndmask_b32_e64 v82, 0, 32, vcc
	v_ldexp_f32 v72, v72, v82
	v_log_f32_e32 v72, v72
	s_nop 0
	v_mul_f32_e32 v82, 0x3f317217, v72
	v_fma_f32 v82, v72, s36, -v82
	v_fmac_f32_e32 v82, 0x3377d1cf, v72
	v_fmac_f32_e32 v82, 0x3f317217, v72
	v_cmp_lt_f32_e64 s[0:1], |v72|, s37
	s_nop 1
	v_cndmask_b32_e64 v72, v72, v82, s[0:1]
	v_cndmask_b32_e32 v82, 0, v232, vcc
	v_sub_f32_e32 v108, v72, v82
.LBB0_292:
	s_andn2_saveexec_b64 s[0:1], s[30:31]
	v_fmamk_f32 v82, v72, 0xbe800000, v226
	v_fma_f32 v82, -v72, v82, 0.5
	v_fma_f32 v82, -v72, v82, 1.0
	v_mul_f32_e32 v108, v72, v82
	s_or_b64 exec, exec, s[0:1]
	v_mul_f32_e32 v72, 0xbfb8aa3b, v201
	v_exp_f32_e32 v72, v72
	s_nop 0
	v_cmp_ngt_f32_e32 vcc, s6, v72
	s_and_saveexec_b64 s[0:1], vcc
	s_xor_b64 s[30:31], exec, s[0:1]
	s_cbranch_execz .LBB0_296
	v_add_f32_e32 v72, 1.0, v72
	v_cmp_gt_f32_e32 vcc, s25, v72
	s_nop 1
	v_cndmask_b32_e64 v73, 0, 32, vcc
	v_ldexp_f32 v72, v72, v73
	v_log_f32_e32 v72, v72
	s_nop 0
	v_mul_f32_e32 v73, 0x3f317217, v72
	v_fma_f32 v73, v72, s36, -v73
	v_fmac_f32_e32 v73, 0x3377d1cf, v72
	v_fmac_f32_e32 v73, 0x3f317217, v72
	v_cmp_lt_f32_e64 s[0:1], |v72|, s37
	s_nop 1
	v_cndmask_b32_e64 v72, v72, v73, s[0:1]
	v_cndmask_b32_e32 v73, 0, v232, vcc
	v_sub_f32_e32 v109, v72, v73
.LBB0_296:
	s_andn2_saveexec_b64 s[0:1], s[30:31]
	v_fmamk_f32 v73, v72, 0xbe800000, v226
	v_fma_f32 v73, -v72, v73, 0.5
	v_fma_f32 v73, -v72, v73, 1.0
	v_mul_f32_e32 v109, v72, v73
	s_or_b64 exec, exec, s[0:1]
	v_mul_f32_e32 v72, 0xbfb8aa3b, v202
	v_exp_f32_e32 v72, v72
	s_nop 0
	v_cmp_ngt_f32_e32 vcc, s6, v72
	s_and_saveexec_b64 s[0:1], vcc
	s_xor_b64 s[30:31], exec, s[0:1]
	s_cbranch_execz .LBB0_300
	v_add_f32_e32 v72, 1.0, v72
	v_cmp_gt_f32_e32 vcc, s25, v72
	s_nop 1
	v_cndmask_b32_e64 v73, 0, 32, vcc
	v_ldexp_f32 v72, v72, v73
	v_log_f32_e32 v72, v72
	s_nop 0
	v_mul_f32_e32 v73, 0x3f317217, v72
	v_fma_f32 v73, v72, s36, -v73
	v_fmac_f32_e32 v73, 0x3377d1cf, v72
	v_fmac_f32_e32 v73, 0x3f317217, v72
	v_cmp_lt_f32_e64 s[0:1], |v72|, s37
	s_nop 1
	v_cndmask_b32_e64 v72, v72, v73, s[0:1]
	v_cndmask_b32_e32 v73, 0, v232, vcc
	v_sub_f32_e32 v110, v72, v73
.LBB0_300:
	s_andn2_saveexec_b64 s[0:1], s[30:31]
	v_fmamk_f32 v73, v72, 0xbe800000, v226
	v_fma_f32 v73, -v72, v73, 0.5
	v_fma_f32 v73, -v72, v73, 1.0
	v_mul_f32_e32 v110, v72, v73
	s_or_b64 exec, exec, s[0:1]
	v_mul_f32_e32 v72, 0xbfb8aa3b, v203
	v_exp_f32_e32 v72, v72
	s_nop 0
	v_cmp_ngt_f32_e32 vcc, s6, v72
	s_and_saveexec_b64 s[0:1], vcc
	s_xor_b64 s[30:31], exec, s[0:1]
	s_cbranch_execz .LBB0_304
	v_add_f32_e32 v72, 1.0, v72
	v_cmp_gt_f32_e32 vcc, s25, v72
	s_nop 1
	v_cndmask_b32_e64 v73, 0, 32, vcc
	v_ldexp_f32 v72, v72, v73
	v_log_f32_e32 v72, v72
	s_nop 0
	v_mul_f32_e32 v73, 0x3f317217, v72
	v_fma_f32 v73, v72, s36, -v73
	v_fmac_f32_e32 v73, 0x3377d1cf, v72
	v_fmac_f32_e32 v73, 0x3f317217, v72
	v_cmp_lt_f32_e64 s[0:1], |v72|, s37
	s_nop 1
	v_cndmask_b32_e64 v72, v72, v73, s[0:1]
	v_cndmask_b32_e32 v73, 0, v232, vcc
	v_sub_f32_e32 v111, v72, v73
; template <int DIR> __device__ __forceinline__ void lru_dir(const Params& p, int l, int n, int h, int lane, LAS bf16_t* XC, LAS float* STA, LAS float* STU) {
;     ...
;     for (int nf = 0; nf < 4; ++nf) {
; #pragma unroll
;         for (int ks = 0; ks < 2; ++ks) { wa[nf][ks] = *(const bf16x8*)(LWa + nf * 1024 + 32 * ks); wx[nf][ks] = *(const bf16x8*)(LWx + nf * 1024 + 32 * ks); }
;         const f32x4 lam4 = *(const f32x4*)(lam + 16 * nf + 4 * q); ba4[nf] = *(const f32x4*)(b_a + 16 * nf + 4 * q); bx4[nf] = *(const f32x4*)(b_x + 16 * nf + 4 * q);
; #pragma unroll
;         for (int r = 0; r < 4; ++r) { const float e = __expf(-lam4[r]); const float l1p = e < 0.05f ? e * (1.0f - e * (0.5f - e * (0.33333334f - e * 0.25f))) : __logf(1.0f + e); sp4[nf][r] = -8.0f * l1p; }
;     }
.LBB0_304:
	s_andn2_saveexec_b64 s[0:1], s[30:31]
	v_fmamk_f32 v73, v72, 0xbe800000, v226
	v_fma_f32 v73, -v72, v73, 0.5
	v_fma_f32 v73, -v72, v73, 1.0
	v_mul_f32_e32 v111, v72, v73
	s_or_b64 exec, exec, s[0:1]
	v_add_co_u32_e32 v80, vcc, 0x1000, v80
	s_nop 1
	v_addc_co_u32_e32 v81, vcc, 0, v81, vcc
	v_add_co_u32_e32 v84, vcc, 0x1000, v78
	s_nop 1
	v_addc_co_u32_e32 v85, vcc, 0, v79, vcc
	global_load_dwordx4 v[72:75], v[80:81], off offset:2048
	s_nop 0
	global_load_dwordx4 v[76:79], v[80:81], off offset:2112
	s_nop 0
	global_load_dwordx4 v[80:83], v[84:85], off offset:2048
	s_nop 0
	global_load_dwordx4 v[84:87], v[84:85], off offset:2112
	s_nop 0
	global_load_dwordx4 v[88:91], v[88:89], off offset:192
	s_nop 0
	global_load_dwordx4 v[92:95], v[92:93], off offset:192
	s_waitcnt vmcnt(6)
	v_mul_f32_e32 v96, 0xbfb8aa3b, v204
	v_exp_f32_e32 v112, v96
	s_nop 0
	v_cmp_ngt_f32_e32 vcc, s6, v112
	s_and_saveexec_b64 s[0:1], vcc
	s_xor_b64 s[30:31], exec, s[0:1]
	s_cbranch_execz .LBB0_308
	v_add_f32_e32 v96, 1.0, v112
	v_cmp_gt_f32_e32 vcc, s25, v96
	s_nop 1
	v_cndmask_b32_e64 v112, 0, 32, vcc
	v_ldexp_f32 v96, v96, v112
	v_log_f32_e32 v96, v96
	s_nop 0
	v_mul_f32_e32 v112, 0x3f317217, v96
	v_fma_f32 v112, v96, s36, -v112
	v_fmac_f32_e32 v112, 0x3377d1cf, v96
	v_fmac_f32_e32 v112, 0x3f317217, v96
	v_cmp_lt_f32_e64 s[0:1], |v96|, s37
	s_nop 1
	v_cndmask_b32_e64 v96, v96, v112, s[0:1]
	v_cndmask_b32_e32 v112, 0, v232, vcc
	v_sub_f32_e32 v96, v96, v112
.LBB0_308:
	s_andn2_saveexec_b64 s[0:1], s[30:31]
	v_fmamk_f32 v96, v112, 0xbe800000, v226
	v_fma_f32 v96, -v112, v96, 0.5
	v_fma_f32 v96, -v112, v96, 1.0
	v_mul_f32_e32 v96, v112, v96
	s_or_b64 exec, exec, s[0:1]
	v_mul_f32_e32 v97, 0xbfb8aa3b, v205
	v_exp_f32_e32 v112, v97
	s_nop 0
	v_cmp_ngt_f32_e32 vcc, s6, v112
	s_and_saveexec_b64 s[0:1], vcc
	s_xor_b64 s[30:31], exec, s[0:1]
	s_cbranch_execz .LBB0_312
	v_add_f32_e32 v97, 1.0, v112
	v_cmp_gt_f32_e32 vcc, s25, v97
	s_nop 1
	v_cndmask_b32_e64 v112, 0, 32, vcc
	v_ldexp_f32 v97, v97, v112
	v_log_f32_e32 v97, v97
	s_nop 0
	v_mul_f32_e32 v112, 0x3f317217, v97
	v_fma_f32 v112, v97, s36, -v112
	v_fmac_f32_e32 v112, 0x3377d1cf, v97
	v_fmac_f32_e32 v112, 0x3f317217, v97
	v_cmp_lt_f32_e64 s[0:1], |v97|, s37
	s_nop 1
	v_cndmask_b32_e64 v97, v97, v112, s[0:1]
	v_cndmask_b32_e32 v112, 0, v232, vcc
	v_sub_f32_e32 v97, v97, v112
.LBB0_312:
	s_andn2_saveexec_b64 s[0:1], s[30:31]
	v_fmamk_f32 v97, v112, 0xbe800000, v226
	v_fma_f32 v97, -v112, v97, 0.5
	v_fma_f32 v97, -v112, v97, 1.0
	v_mul_f32_e32 v97, v112, v97
	s_or_b64 exec, exec, s[0:1]
	v_mul_f32_e32 v98, 0xbfb8aa3b, v206
	v_exp_f32_e32 v112, v98
	s_nop 0
	v_cmp_ngt_f32_e32 vcc, s6, v112
	s_and_saveexec_b64 s[0:1], vcc
	s_xor_b64 s[30:31], exec, s[0:1]
	s_cbranch_execz .LBB0_316
	v_add_f32_e32 v98, 1.0, v112
	v_cmp_gt_f32_e32 vcc, s25, v98
	s_nop 1
	v_cndmask_b32_e64 v112, 0, 32, vcc
	v_ldexp_f32 v98, v98, v112
	v_log_f32_e32 v98, v98
	s_nop 0
	v_mul_f32_e32 v112, 0x3f317217, v98
	v_fma_f32 v112, v98, s36, -v112
	v_fmac_f32_e32 v112, 0x3377d1cf, v98
	v_fmac_f32_e32 v112, 0x3f317217, v98
	v_cmp_lt_f32_e64 s[0:1], |v98|, s37
	s_nop 1
	v_cndmask_b32_e64 v98, v98, v112, s[0:1]
	v_cndmask_b32_e32 v112, 0, v232, vcc
	v_sub_f32_e32 v98, v98, v112
.LBB0_316:
	s_andn2_saveexec_b64 s[0:1], s[30:31]
	v_fmamk_f32 v98, v112, 0xbe800000, v226
	v_fma_f32 v98, -v112, v98, 0.5
	v_fma_f32 v98, -v112, v98, 1.0
	v_mul_f32_e32 v98, v112, v98
	s_or_b64 exec, exec, s[0:1]
	v_mul_f32_e32 v99, 0xbfb8aa3b, v207
	v_exp_f32_e32 v112, v99
	s_nop 0
	v_cmp_ngt_f32_e32 vcc, s6, v112
	s_and_saveexec_b64 s[0:1], vcc
	s_xor_b64 s[30:31], exec, s[0:1]
	s_cbranch_execz .LBB0_320
	v_add_f32_e32 v99, 1.0, v112
	v_cmp_gt_f32_e32 vcc, s25, v99
	s_nop 1
	v_cndmask_b32_e64 v112, 0, 32, vcc
	v_ldexp_f32 v99, v99, v112
	v_log_f32_e32 v99, v99
	s_nop 0
	v_mul_f32_e32 v112, 0x3f317217, v99
	v_fma_f32 v112, v99, s36, -v112
	v_fmac_f32_e32 v112, 0x3377d1cf, v99
	v_fmac_f32_e32 v112, 0x3f317217, v99
	v_cmp_lt_f32_e64 s[0:1], |v99|, s37
	s_nop 1
	v_cndmask_b32_e64 v99, v99, v112, s[0:1]
	v_cndmask_b32_e32 v112, 0, v232, vcc
	v_sub_f32_e32 v99, v99, v112
